# cross-attention LDS fixes: K-tile 16B-chunk XOR swizzle (2-way bank conflict removed), V^T ds_read2_b64 split into 2x ds_read_b64 in loop and peeled tile (address/dest overlap pair reordered)
# speedup vs baseline: 1.0259x; 1.0071x over previous
; #define LAS __attribute__((address_space(3)))
; template <int D, int DV, int MODE, int NMAP, int KT> ...
;     ...
;         if (MODE == 0 || kt * KT <= rowmin + 15) {
;             const LAS bf16_t* Ks = (const LAS bf16_t*)(lds + cur); const LAS bf16_t* Vt = (const LAS bf16_t*)(lds + cur + KS_BYTES);
;             const bool diag = (MODE != 0) && (kt * KT + KT - 1 > rowmin);
;             bf16x8 pb[NMAP][KK2];
;             f32x4 sall[NMAP][NB];
; #pragma unroll
;             for (int mp = 0; mp < NMAP; ++mp) {
;                 f32x4 (&s)[NB] = sall[mp];
;                 constexpr int KD = D / 32, NBB = (KD >= 8) ? 1 : (8 / KD), NSB = NB / NBB;
;                 bf16x8 kfr[2][NBB][KD];
;     ...
;                 AT_SLOAD(0, 0);
; #pragma unroll
;                 for (int bi = 0; bi < NSB; ++bi) {
;                     if (bi + 1 < NSB) AT_SLOAD(bi + 1, (bi + 1) & 1);
;                     __builtin_amdgcn_sched_barrier(0);
;                     __builtin_amdgcn_s_setprio(1);
; #pragma unroll
;                     for (int x_ = 0; x_ < NBB; ++x_) { const int nb = bi * NBB + x_;
;                         s[nb] = __builtin_amdgcn_mfma_f32_16x16x32_bf16(kfr[bi & 1][x_][0], qf[mp][0], (f32x4){0.f, 0.f, 0.f, 0.f}, 0, 0, 0);
; #pragma unroll
;                         for (int kk = 1; kk < KD; ++kk) s[nb] = __builtin_amdgcn_mfma_f32_16x16x32_bf16(kfr[bi & 1][x_][kk], qf[mp][kk], s[nb], 0, 0, 0); }
;                     __builtin_amdgcn_s_setprio(0);
;                     __builtin_amdgcn_sched_barrier(0);
;                 }
;     ...
;             }
; #pragma unroll
;             for (int mp = 0; mp < NMAP; ++mp) {
;                 f32x4 (&s)[NB] = sall[mp];
;                 if (MODE < 2) {
;                     if (diag) {
; #pragma unroll
;                         for (int nb = 0; nb < NB; ++nb)
; #pragma unroll
;                             for (int j = 0; j < 4; ++j) { if (kt * KT + nb * 16 + g4 * 4 + j > myrow) s[nb][j] = -INFINITY; }
;                     }
;                     float mx = fmaxf(fmaxf(s[0][0], s[0][1]), s[0][2]);
;                     mx = fmaxf(fmaxf(mx, s[0][3]), s[1][0]); mx = fmaxf(fmaxf(mx, s[1][1]), s[1][2]); mx = fmaxf(fmaxf(mx, s[1][3]), s[2][0]);
;                     mx = fmaxf(fmaxf(mx, s[2][1]), s[2][2]); mx = fmaxf(fmaxf(mx, s[2][3]), s[3][0]); mx = fmaxf(fmaxf(mx, s[3][1]), s[3][2]); mx = fmaxf(mx, s[3][3]);
; #pragma unroll
.LBB0_597:
	s_add_i32 s6, 0, 0x11400
	v_or_b32_e32 v130, 16, v160
	v_lshl_add_u32 v131, v158, 1, s6
	s_waitcnt vmcnt(0)
	v_add_u32_e32 v126, v131, v170
	v_add_u32_e32 v148, 0x2100, v126
	s_barrier
	ds_read_b128 v[98:101], v126
	ds_read_b128 v[102:105], v126 offset:64
	ds_read_b128 v[106:109], v126 offset:128
	ds_read_b128 v[110:113], v126 offset:192
	ds_read_b128 v[114:117], v126 offset:256
	ds_read_b128 v[118:121], v126 offset:320
	ds_read_b128 v[122:125], v126 offset:384
	ds_read_b128 v[126:129], v126 offset:448
	ds_read_b128 v[130:133], v148
	ds_read_b128 v[134:137], v148 offset:64
	ds_read_b128 v[138:141], v148 offset:128
	ds_read_b128 v[142:145], v148 offset:192
	ds_read_b128 v[150:153], v148 offset:256
	ds_read_b128 v[154:157], v148 offset:320
	ds_read_b128 v[160:163], v148 offset:384
	ds_read_b128 v[164:167], v148 offset:448
	s_setprio 1
	s_waitcnt lgkmcnt(14)
	v_mfma_f32_16x16x32_bf16 v[98:101], v[98:101], v[66:69], 0
	v_mfma_f32_16x16x32_bf16 v[98:101], v[102:105], v[70:73], v[98:101]
	s_waitcnt lgkmcnt(13)
	v_mfma_f32_16x16x32_bf16 v[98:101], v[106:109], v[74:77], v[98:101]
	s_waitcnt lgkmcnt(12)
	v_mfma_f32_16x16x32_bf16 v[98:101], v[110:113], v[78:81], v[98:101]
	s_waitcnt lgkmcnt(11)
	v_mfma_f32_16x16x32_bf16 v[98:101], v[114:117], v[82:85], v[98:101]
	s_waitcnt lgkmcnt(10)
	v_mfma_f32_16x16x32_bf16 v[98:101], v[118:121], v[86:89], v[98:101]
	s_waitcnt lgkmcnt(9)
	v_mfma_f32_16x16x32_bf16 v[98:101], v[122:125], v[90:93], v[98:101]
	s_waitcnt lgkmcnt(8)
	v_mfma_f32_16x16x32_bf16 v[106:109], v[126:129], v[94:97], v[98:101]
	s_setprio 0
	s_nop 4
	ds_read_b128 v[98:101], v148 offset:8448
	ds_read_b128 v[110:113], v148 offset:8512
	ds_read_b128 v[114:117], v148 offset:8576
	ds_read_b128 v[118:121], v148 offset:8640
	ds_read_b128 v[122:125], v148 offset:8704
	ds_read_b128 v[126:129], v148 offset:8768
	ds_read_b128 v[168:171], v148 offset:8832
	ds_read_b128 v[176:179], v148 offset:8896
	s_setprio 1
	s_waitcnt lgkmcnt(14)
	v_mfma_f32_16x16x32_bf16 v[102:105], v[130:133], v[66:69], 0
	v_mfma_f32_16x16x32_bf16 v[102:105], v[134:137], v[70:73], v[102:105]
	s_waitcnt lgkmcnt(13)
	v_mfma_f32_16x16x32_bf16 v[102:105], v[138:141], v[74:77], v[102:105]
	s_waitcnt lgkmcnt(12)
	v_mfma_f32_16x16x32_bf16 v[102:105], v[142:145], v[78:81], v[102:105]
	s_waitcnt lgkmcnt(11)
	v_mfma_f32_16x16x32_bf16 v[102:105], v[150:153], v[82:85], v[102:105]
	s_waitcnt lgkmcnt(10)
	v_mfma_f32_16x16x32_bf16 v[102:105], v[154:157], v[86:89], v[102:105]
	s_waitcnt lgkmcnt(9)
	v_mfma_f32_16x16x32_bf16 v[102:105], v[160:163], v[90:93], v[102:105]
	s_waitcnt lgkmcnt(8)
	v_mfma_f32_16x16x32_bf16 v[102:105], v[164:167], v[94:97], v[102:105]
	s_setprio 0
	ds_read_b128 v[130:133], v148 offset:16896
	ds_read_b128 v[134:137], v148 offset:16960
	ds_read_b128 v[138:141], v148 offset:17024
	ds_read_b128 v[142:145], v148 offset:17088
	ds_read_b128 v[150:153], v148 offset:17152
	ds_read_b128 v[154:157], v148 offset:17216
	ds_read_b128 v[160:163], v148 offset:17280
	ds_read_b128 v[164:167], v148 offset:17344
	s_setprio 1
	s_waitcnt lgkmcnt(14)
	v_mfma_f32_16x16x32_bf16 v[98:101], v[98:101], v[66:69], 0
	v_mfma_f32_16x16x32_bf16 v[98:101], v[110:113], v[70:73], v[98:101]
	s_waitcnt lgkmcnt(13)
	v_mfma_f32_16x16x32_bf16 v[98:101], v[114:117], v[74:77], v[98:101]
	s_waitcnt lgkmcnt(12)
	v_mfma_f32_16x16x32_bf16 v[98:101], v[118:121], v[78:81], v[98:101]
	s_waitcnt lgkmcnt(11)
	v_mfma_f32_16x16x32_bf16 v[98:101], v[122:125], v[82:85], v[98:101]
	s_waitcnt lgkmcnt(10)
	v_mfma_f32_16x16x32_bf16 v[98:101], v[126:129], v[86:89], v[98:101]
	s_waitcnt lgkmcnt(9)
	v_mfma_f32_16x16x32_bf16 v[98:101], v[168:171], v[90:93], v[98:101]
	s_waitcnt lgkmcnt(8)
	v_mfma_f32_16x16x32_bf16 v[98:101], v[176:179], v[94:97], v[98:101]
	s_setprio 0
	s_setprio 1
	s_waitcnt lgkmcnt(7)
	v_mfma_f32_16x16x32_bf16 v[66:69], v[130:133], v[66:69], 0
	s_waitcnt lgkmcnt(6)
	v_mfma_f32_16x16x32_bf16 v[66:69], v[134:137], v[70:73], v[66:69]
	s_waitcnt lgkmcnt(5)
	v_mfma_f32_16x16x32_bf16 v[66:69], v[138:141], v[74:77], v[66:69]
	s_waitcnt lgkmcnt(4)
	v_mfma_f32_16x16x32_bf16 v[66:69], v[142:145], v[78:81], v[66:69]
	s_waitcnt lgkmcnt(3)
	v_mfma_f32_16x16x32_bf16 v[66:69], v[150:153], v[82:85], v[66:69]
	s_waitcnt lgkmcnt(2)
	v_mfma_f32_16x16x32_bf16 v[66:69], v[154:157], v[86:89], v[66:69]
	s_waitcnt lgkmcnt(1)
	v_mfma_f32_16x16x32_bf16 v[66:69], v[160:163], v[90:93], v[66:69]
	s_waitcnt lgkmcnt(0)
	v_mfma_f32_16x16x32_bf16 v[66:69], v[164:167], v[94:97], v[66:69]
	s_setprio 0
	v_max_f32_e32 v70, v107, v107
	v_max_f32_e32 v71, v106, v106
	v_max_f32_e32 v70, v71, v70
	v_max3_f32 v70, v70, v108, v109
	v_max3_f32 v70, v70, v102, v103
	v_max3_f32 v70, v70, v104, v105
	v_max3_f32 v70, v70, v98, v99
	v_max3_f32 v70, v70, v100, v101
	v_max3_f32 v70, v70, v66, v67
	v_max3_f32 v70, v70, v68, v69
	v_mov_b32_e32 v71, v70
	s_nop 1
	v_permlane16_swap_b32_e32 v70, v71
	v_max_f32_e32 v71, v71, v71
	v_max_f32_e32 v70, v70, v70
	v_max_f32_e32 v70, v70, v71
	v_mov_b32_e32 v71, v70
	s_nop 1
	v_permlane32_swap_b32_e32 v70, v71
	v_max_f32_e32 v71, v71, v71
	v_max_f32_e32 v70, v70, v70
	v_max_f32_e32 v70, v70, v71
	v_mul_f32_e32 v70, 0x3db8aa3b, v70
	v_add_f32_e32 v71, 0x40c00000, v175
	v_cmp_gt_f32_e32 vcc, v70, v71
	s_cbranch_vccz .LBB0_607
; template <int D, int DV, int MODE, int NMAP, int KT> ...
;     ...
;                     if (__any(mx > m[mp] + 6.0f)) {
;                         const float mn = fmaxf(m[mp], mx); const float al = __builtin_amdgcn_exp2f(m[mp] - mn); m[mp] = mn; l[mp] *= al;
; #pragma unroll
;                         for (int cb = 0; cb < DV / 16; ++cb) o[mp][cb] = o[mp][cb] * al;
;                     }
;                     const float nm = -m[mp]; float ps = 0.f;
; #pragma unroll
;                     for (int nb = 0; nb < NB; ++nb)
; #pragma unroll
;                         for (int j = 0; j < 4; ++j) { const float p = __builtin_amdgcn_exp2f(fmaf(s[nb][j], sc, nm)); ps += p; s[nb][j] = p; }
;                     l[mp] += ps;
;                 } else {
;                     const float rowf = __builtin_amdgcn_exp2f(l2g * (float)(myrow - kt * KT));
; #pragma unroll
;                     for (int nb = 0; nb < NB; ++nb)
; #pragma unroll
;                         for (int j = 0; j < 4; ++j) { float p = s[nb][j] * (rowf * ck[nb][j]); if (diag && (kt * KT + nb * 16 + g4 * 4 + j > myrow)) p = 0.f; s[nb][j] = p; }
;                 }
; #pragma unroll
;                 for (int kk = 0; kk < KK2; ++kk) { u32x4 wv; wv.x = cvt_pk_bf16(s[2 * kk][0], s[2 * kk][1]); wv.y = cvt_pk_bf16(s[2 * kk][2], s[2 * kk][3]);
;                     wv.z = cvt_pk_bf16(s[2 * kk + 1][0], s[2 * kk + 1][1]); wv.w = cvt_pk_bf16(s[2 * kk + 1][2], s[2 * kk + 1][3]); pb[mp][kk] = __builtin_bit_cast(bf16x8, wv); }
;             }
;             {
;                 constexpr int CBB = 4, NCB = (DV / 16) / CBB, NVB = KK2 * NCB;
;                 bf16x8 vfr[2][CBB];
;     ...
;                 AT_VLOAD(0, 0);
; #pragma unroll
;                 for (int b_ = 0; b_ < NVB; ++b_) {
;                     if (b_ + 1 < NVB) AT_VLOAD(b_ + 1, (b_ + 1) & 1);
;                     __builtin_amdgcn_sched_barrier(0);
;                     const int kk_ = b_ / NCB, c0_ = (b_ % NCB) * CBB;
;                     __builtin_amdgcn_s_setprio(1);
; #pragma unroll
;                     for (int x_ = 0; x_ < CBB; ++x_)
; #pragma unroll
;                         for (int mp = 0; mp < NMAP; ++mp) o[mp][c0_ + x_] = __builtin_amdgcn_mfma_f32_16x16x32_bf16(vfr[b_ & 1][x_], pb[mp][kk_], o[mp][c0_ + x_], 0, 0, 0);
;                     __builtin_amdgcn_s_setprio(0);
;                     __builtin_amdgcn_sched_barrier(0);
;                 }
	v_max_f32_e64 v70, -v70, -v70
	v_max_f32_e64 v71, -v175, -v175
	v_min_f32_e32 v70, v71, v70
	v_add_f32_e32 v71, v175, v70
	v_exp_f32_e32 v72, v71
	s_nop 0
	v_mul_f32_e32 v159, v159, v72
	v_pk_mul_f32 v[64:65], v[64:65], v[72:73] op_sel_hi:[1,0]
	v_pk_mul_f32 v[62:63], v[62:63], v[72:73] op_sel_hi:[1,0]
	v_pk_mul_f32 v[60:61], v[60:61], v[72:73] op_sel_hi:[1,0]
	v_pk_mul_f32 v[58:59], v[58:59], v[72:73] op_sel_hi:[1,0]
	v_pk_mul_f32 v[56:57], v[56:57], v[72:73] op_sel_hi:[1,0]
	v_pk_mul_f32 v[54:55], v[54:55], v[72:73] op_sel_hi:[1,0]
	v_pk_mul_f32 v[52:53], v[52:53], v[72:73] op_sel_hi:[1,0]
	v_pk_mul_f32 v[50:51], v[50:51], v[72:73] op_sel_hi:[1,0]
	v_pk_mul_f32 v[48:49], v[48:49], v[72:73] op_sel_hi:[1,0]
	v_pk_mul_f32 v[46:47], v[46:47], v[72:73] op_sel_hi:[1,0]
	v_pk_mul_f32 v[44:45], v[44:45], v[72:73] op_sel_hi:[1,0]
	v_pk_mul_f32 v[42:43], v[42:43], v[72:73] op_sel_hi:[1,0]
	v_pk_mul_f32 v[40:41], v[40:41], v[72:73] op_sel_hi:[1,0]
	v_pk_mul_f32 v[38:39], v[38:39], v[72:73] op_sel_hi:[1,0]
	v_pk_mul_f32 v[36:37], v[36:37], v[72:73] op_sel_hi:[1,0]
	v_pk_mul_f32 v[34:35], v[34:35], v[72:73] op_sel_hi:[1,0]
	v_pk_mul_f32 v[32:33], v[32:33], v[72:73] op_sel_hi:[1,0]
	v_pk_mul_f32 v[30:31], v[30:31], v[72:73] op_sel_hi:[1,0]
	v_pk_mul_f32 v[28:29], v[28:29], v[72:73] op_sel_hi:[1,0]
	v_pk_mul_f32 v[26:27], v[26:27], v[72:73] op_sel_hi:[1,0]
	v_pk_mul_f32 v[24:25], v[24:25], v[72:73] op_sel_hi:[1,0]
	v_pk_mul_f32 v[22:23], v[22:23], v[72:73] op_sel_hi:[1,0]
	v_pk_mul_f32 v[20:21], v[20:21], v[72:73] op_sel_hi:[1,0]
	v_pk_mul_f32 v[18:19], v[18:19], v[72:73] op_sel_hi:[1,0]
	v_pk_mul_f32 v[16:17], v[16:17], v[72:73] op_sel_hi:[1,0]
	v_pk_mul_f32 v[14:15], v[14:15], v[72:73] op_sel_hi:[1,0]
	v_pk_mul_f32 v[12:13], v[12:13], v[72:73] op_sel_hi:[1,0]
	v_pk_mul_f32 v[10:11], v[10:11], v[72:73] op_sel_hi:[1,0]
	v_pk_mul_f32 v[8:9], v[8:9], v[72:73] op_sel_hi:[1,0]
	v_pk_mul_f32 v[6:7], v[6:7], v[72:73] op_sel_hi:[1,0]
	v_pk_mul_f32 v[4:5], v[4:5], v[72:73] op_sel_hi:[1,0]
	v_pk_mul_f32 v[2:3], v[2:3], v[72:73] op_sel_hi:[1,0]
.LBB0_599:
	v_fmamk_f32 v71, v106, 0x3db8aa3b, v70
	v_exp_f32_e32 v71, v71
	v_fmamk_f32 v73, v107, 0x3db8aa3b, v70
	v_exp_f32_e32 v73, v73
	v_fmamk_f32 v74, v108, 0x3db8aa3b, v70
	v_exp_f32_e32 v74, v74
	v_fmamk_f32 v75, v109, 0x3db8aa3b, v70
	v_exp_f32_e32 v75, v75
	v_fmamk_f32 v76, v102, 0x3db8aa3b, v70
	v_add_f32_e32 v72, 0, v71
	v_exp_f32_e32 v76, v76
	v_fmamk_f32 v77, v103, 0x3db8aa3b, v70
	v_add_f32_e32 v72, v73, v72
	v_exp_f32_e32 v77, v77
	v_fmamk_f32 v78, v104, 0x3db8aa3b, v70
	v_add_f32_e32 v72, v74, v72
	v_exp_f32_e32 v78, v78
	v_fmamk_f32 v79, v105, 0x3db8aa3b, v70
	v_add_f32_e32 v72, v75, v72
	v_exp_f32_e32 v79, v79
	v_fmamk_f32 v80, v98, 0x3db8aa3b, v70
	v_add_f32_e32 v72, v76, v72
	v_exp_f32_e32 v80, v80
	v_fmamk_f32 v81, v99, 0x3db8aa3b, v70
	v_add_f32_e32 v72, v77, v72
	v_exp_f32_e32 v81, v81
	v_fmamk_f32 v82, v100, 0x3db8aa3b, v70
	v_add_f32_e32 v72, v78, v72
	v_exp_f32_e32 v82, v82
	v_fmamk_f32 v83, v101, 0x3db8aa3b, v70
	v_add_f32_e32 v72, v79, v72
	v_exp_f32_e32 v83, v83
	v_fmamk_f32 v66, v66, 0x3db8aa3b, v70
	v_add_f32_e32 v72, v80, v72
	v_exp_f32_e32 v84, v66
	v_fmamk_f32 v67, v67, 0x3db8aa3b, v70
	v_add_f32_e32 v72, v81, v72
	v_exp_f32_e32 v85, v67
	v_fmamk_f32 v67, v68, 0x3db8aa3b, v70
	v_add_f32_e32 v72, v82, v72
	v_exp_f32_e32 v86, v67
	v_fmac_f32_e32 v70, 0x3db8aa3b, v69
	v_add_f32_e32 v72, v83, v72
	v_exp_f32_e32 v69, v70
	v_add_f32_e32 v66, v84, v72
	v_add_f32_e32 v66, v85, v66
	v_readlane_b32 s6, v255, 12
	v_add_f32_e32 v66, v86, v66
	v_add_f32_e32 v66, v69, v66
	v_add3_u32 v107, s6, v158, v149
	v_add_u32_e32 v108, 0x800, v107
	v_add_u32_e32 v109, 0x1000, v107
	v_add_u32_e32 v110, 0x1800, v107
	v_add_u32_e32 v111, 0x2000, v107
	v_add_u32_e32 v112, 0x2800, v107
	v_add_u32_e32 v113, 0x3000, v107
	v_add_u32_e32 v114, 0x3800, v107
	v_add_f32_e32 v106, v159, v66
	v_cvt_pk_bf16_f32 v70, v71, v73
	v_cvt_pk_bf16_f32 v71, v74, v75
	v_cvt_pk_bf16_f32 v72, v76, v77
	v_cvt_pk_bf16_f32 v73, v78, v79
	v_cvt_pk_bf16_f32 v66, v80, v81
	v_cvt_pk_bf16_f32 v67, v82, v83
	v_cvt_pk_bf16_f32 v68, v84, v85
	v_cvt_pk_bf16_f32 v69, v86, v69
	ds_read_b64 v[74:75], v107
	ds_read_b64 v[76:77], v107 offset:32
	ds_read_b64 v[78:79], v108 offset:256
	ds_read_b64 v[80:81], v108 offset:288
	ds_read_b64 v[82:83], v109 offset:512
	ds_read_b64 v[84:85], v109 offset:544
	ds_read_b64 v[86:87], v110 offset:768
	ds_read_b64 v[88:89], v110 offset:800
	ds_read_b64 v[90:91], v111 offset:1024
	ds_read_b64 v[92:93], v111 offset:1056
	ds_read_b64 v[94:95], v112 offset:1280
	ds_read_b64 v[96:97], v112 offset:1312
	ds_read_b64 v[98:99], v113 offset:1536
	ds_read_b64 v[100:101], v113 offset:1568
	ds_read_b64 v[102:103], v114 offset:1792
	ds_read_b64 v[104:105], v114 offset:1824
	s_mov_b64 s[42:43], 0x800
	s_setprio 1
	s_waitcnt lgkmcnt(14)
	v_mfma_f32_16x16x32_bf16 v[62:65], v[74:77], v[70:73], v[62:65]
	s_waitcnt lgkmcnt(12)
	v_mfma_f32_16x16x32_bf16 v[58:61], v[78:81], v[70:73], v[58:61]
	s_waitcnt lgkmcnt(10)
	v_mfma_f32_16x16x32_bf16 v[54:57], v[82:85], v[70:73], v[54:57]
	s_waitcnt lgkmcnt(8)
	v_mfma_f32_16x16x32_bf16 v[50:53], v[86:89], v[70:73], v[50:53]
	s_setprio 0
	v_add_u32_e32 v115, 0x4800, v107
	v_add_u32_e32 v116, 0x5000, v107
	v_add_u32_e32 v117, 0x5800, v107
	v_add_u32_e32 v118, 0x6000, v107
	ds_read_b64 v[74:75], v115
	ds_read_b64 v[76:77], v115 offset:32
	ds_read_b64 v[78:79], v116 offset:256
	ds_read_b64 v[80:81], v116 offset:288
	ds_read_b64 v[82:83], v117 offset:512
	ds_read_b64 v[84:85], v117 offset:544
	ds_read_b64 v[86:87], v118 offset:768
	ds_read_b64 v[88:89], v118 offset:800
	s_setprio 1
	s_waitcnt lgkmcnt(14)
; template <int D, int DV, int MODE, int NMAP, int KT> ...
;     ...
;                 constexpr int CBB = 4, NCB = (DV / 16) / CBB, NVB = KK2 * NCB;
;                 bf16x8 vfr[2][CBB];
;     ...
;                 AT_VLOAD(0, 0);
; #pragma unroll
;                 for (int b_ = 0; b_ < NVB; ++b_) {
;                     if (b_ + 1 < NVB) AT_VLOAD(b_ + 1, (b_ + 1) & 1);
;                     __builtin_amdgcn_sched_barrier(0);
;                     const int kk_ = b_ / NCB, c0_ = (b_ % NCB) * CBB;
;                     __builtin_amdgcn_s_setprio(1);
; #pragma unroll
;                     for (int x_ = 0; x_ < CBB; ++x_)
; #pragma unroll
;                         for (int mp = 0; mp < NMAP; ++mp) o[mp][c0_ + x_] = __builtin_amdgcn_mfma_f32_16x16x32_bf16(vfr[b_ & 1][x_], pb[mp][kk_], o[mp][c0_ + x_], 0, 0, 0);
;                     __builtin_amdgcn_s_setprio(0);
;                     __builtin_amdgcn_sched_barrier(0);
;                 }
	v_mfma_f32_16x16x32_bf16 v[46:49], v[90:93], v[70:73], v[46:49]
	s_waitcnt lgkmcnt(12)
	v_mfma_f32_16x16x32_bf16 v[42:45], v[94:97], v[70:73], v[42:45]
	s_waitcnt lgkmcnt(10)
	v_mfma_f32_16x16x32_bf16 v[38:41], v[98:101], v[70:73], v[38:41]
	s_waitcnt lgkmcnt(8)
	v_mfma_f32_16x16x32_bf16 v[34:37], v[102:105], v[70:73], v[34:37]
	s_setprio 0
	v_add_u32_e32 v119, 0x6800, v107
	v_add_u32_e32 v120, 0x7000, v107
	v_add_u32_e32 v121, 0x7800, v107
	v_add_u32_e32 v122, 0x8000, v107
	ds_read_b64 v[90:91], v119 offset:1024
	ds_read_b64 v[92:93], v119 offset:1056
	ds_read_b64 v[94:95], v120 offset:1280
	ds_read_b64 v[96:97], v120 offset:1312
	ds_read_b64 v[98:99], v121 offset:1536
	ds_read_b64 v[100:101], v121 offset:1568
	ds_read_b64 v[102:103], v122 offset:1792
	ds_read_b64 v[104:105], v122 offset:1824
	s_setprio 1
	s_waitcnt lgkmcnt(14)
	v_mfma_f32_16x16x32_bf16 v[30:33], v[74:77], v[70:73], v[30:33]
	s_waitcnt lgkmcnt(12)
	v_mfma_f32_16x16x32_bf16 v[26:29], v[78:81], v[70:73], v[26:29]
	s_waitcnt lgkmcnt(10)
	v_mfma_f32_16x16x32_bf16 v[22:25], v[82:85], v[70:73], v[22:25]
	s_waitcnt lgkmcnt(8)
	v_mfma_f32_16x16x32_bf16 v[18:21], v[86:89], v[70:73], v[18:21]
	s_setprio 0
	ds_read_b64 v[74:75], v107 offset:64
	ds_read_b64 v[76:77], v107 offset:96
	ds_read_b64 v[78:79], v108 offset:320
	ds_read_b64 v[80:81], v108 offset:352
	ds_read_b64 v[82:83], v109 offset:576
	ds_read_b64 v[84:85], v109 offset:608
	ds_read_b64 v[86:87], v110 offset:832
	ds_read_b64 v[88:89], v110 offset:864
	s_setprio 1
	s_waitcnt lgkmcnt(14)
	v_mfma_f32_16x16x32_bf16 v[14:17], v[90:93], v[70:73], v[14:17]
	s_waitcnt lgkmcnt(12)
	v_mfma_f32_16x16x32_bf16 v[10:13], v[94:97], v[70:73], v[10:13]
	s_waitcnt lgkmcnt(10)
	v_mfma_f32_16x16x32_bf16 v[6:9], v[98:101], v[70:73], v[6:9]
	s_waitcnt lgkmcnt(8)
	v_mfma_f32_16x16x32_bf16 v[2:5], v[102:105], v[70:73], v[2:5]
	s_setprio 0
	ds_read_b64 v[70:71], v111 offset:1088
	ds_read_b64 v[72:73], v111 offset:1120
	ds_read_b64 v[90:91], v112 offset:1344
	ds_read_b64 v[92:93], v112 offset:1376
	ds_read_b64 v[94:95], v113 offset:1600
	ds_read_b64 v[96:97], v113 offset:1632
	ds_read_b64 v[98:99], v114 offset:1856
	ds_read_b64 v[100:101], v114 offset:1888
	s_setprio 1
	s_waitcnt lgkmcnt(14)
	v_mfma_f32_16x16x32_bf16 v[62:65], v[74:77], v[66:69], v[62:65]
	s_waitcnt lgkmcnt(12)
	v_mfma_f32_16x16x32_bf16 v[58:61], v[78:81], v[66:69], v[58:61]
	s_waitcnt lgkmcnt(10)
	v_mfma_f32_16x16x32_bf16 v[54:57], v[82:85], v[66:69], v[54:57]
	s_waitcnt lgkmcnt(8)
	v_mfma_f32_16x16x32_bf16 v[50:53], v[86:89], v[66:69], v[50:53]
	s_setprio 0
	ds_read_b64 v[74:75], v115 offset:64
	ds_read_b64 v[76:77], v115 offset:96
	ds_read_b64 v[78:79], v116 offset:320
	ds_read_b64 v[80:81], v116 offset:352
	ds_read_b64 v[82:83], v117 offset:576
	ds_read_b64 v[84:85], v117 offset:608
	ds_read_b64 v[86:87], v118 offset:832
	ds_read_b64 v[88:89], v118 offset:864
	s_setprio 1
	s_waitcnt lgkmcnt(14)
	v_mfma_f32_16x16x32_bf16 v[46:49], v[70:73], v[66:69], v[46:49]
	s_waitcnt lgkmcnt(12)
	v_mfma_f32_16x16x32_bf16 v[42:45], v[90:93], v[66:69], v[42:45]
	s_waitcnt lgkmcnt(10)
	v_mfma_f32_16x16x32_bf16 v[38:41], v[94:97], v[66:69], v[38:41]
	s_waitcnt lgkmcnt(8)
	v_mfma_f32_16x16x32_bf16 v[34:37], v[98:101], v[66:69], v[34:37]
	s_setprio 0
	ds_read_b64 v[70:71], v119 offset:1088
	ds_read_b64 v[72:73], v119 offset:1120
	ds_read_b64 v[90:91], v120 offset:1344
	ds_read_b64 v[92:93], v120 offset:1376
	ds_read_b64 v[94:95], v121 offset:1600
	ds_read_b64 v[96:97], v121 offset:1632
	ds_read_b64 v[98:99], v122 offset:1856
	ds_read_b64 v[100:101], v122 offset:1888
	s_setprio 1
	s_waitcnt lgkmcnt(14)
	v_mfma_f32_16x16x32_bf16 v[30:33], v[74:77], v[66:69], v[30:33]
	s_waitcnt lgkmcnt(12)
	v_mfma_f32_16x16x32_bf16 v[26:29], v[78:81], v[66:69], v[26:29]
	s_waitcnt lgkmcnt(10)
	v_mfma_f32_16x16x32_bf16 v[22:25], v[82:85], v[66:69], v[22:25]
	s_waitcnt lgkmcnt(8)
	v_mfma_f32_16x16x32_bf16 v[18:21], v[86:89], v[66:69], v[18:21]
	s_setprio 0
	s_setprio 1
	s_waitcnt lgkmcnt(6)
	v_mfma_f32_16x16x32_bf16 v[14:17], v[70:73], v[66:69], v[14:17]
	s_waitcnt lgkmcnt(4)
	v_mfma_f32_16x16x32_bf16 v[10:13], v[90:93], v[66:69], v[10:13]
	s_waitcnt lgkmcnt(2)
	v_mfma_f32_16x16x32_bf16 v[6:9], v[94:97], v[66:69], v[6:9]
	s_waitcnt lgkmcnt(0)
; __device__ __forceinline__ float xsum_rows(float v) { return xsum32(xsum16(v)); }
; __device__ __forceinline__ unsigned cvt_pk_bf16(float lo, float hi) { unsigned r; asm volatile("v_cvt_pk_bf16_f32 %0, %1, %2" : "=v"(r) : "v"(lo), "v"(hi)); return r; }
; template <int D, int DV, int MODE, int NMAP, int KT> ...
;     ...
;     if (MODE < 2) {
; #pragma unroll
;         for (int mp = 0; mp < NMAP; ++mp) l[mp] = xsum_rows(l[mp]);
; __global__ void __launch_bounds__(512, 2) mega_fwd(Params P) {
;     ...
;                         const float iv = 1.0f / ll[0]; const size_t row = rb + q0 + wave * 16 + r;
; #pragma unroll
;                         for (int cb = 0; cb < 16; ++cb) { const f32x4 v = o[0][cb] * iv; u32x2 wv; wv.x = cvt_pk_bf16(v[0], v[1]); wv.y = cvt_pk_bf16(v[2], v[3]);
;                             *(u32x2*)(CAT + row * 1024 + h * 256 + cb * 16 + g4 * 4) = wv; }
	v_mfma_f32_16x16x32_bf16 v[2:5], v[98:101], v[66:69], v[2:5]
	s_setprio 0
	v_mov_b32_e32 v66, v106
	s_nop 1
	v_permlane16_swap_b32_e32 v106, v66
	v_add_f32_e32 v66, v106, v66
	v_mov_b32_e32 v67, v66
	s_nop 1
	v_permlane32_swap_b32_e32 v66, v67
	v_add_f32_e32 v66, v66, v67
	v_div_scale_f32 v67, s[6:7], v66, v66, 1.0
	v_rcp_f32_e32 v68, v67
	s_nop 0
	v_fma_f32 v69, -v67, v68, 1.0
	v_fmac_f32_e32 v68, v69, v68
	v_div_scale_f32 v69, vcc, 1.0, v66, 1.0
	v_mul_f32_e32 v70, v69, v68
	v_fma_f32 v71, -v67, v70, v69
	v_fmac_f32_e32 v70, v71, v68
	v_fma_f32 v67, -v67, v70, v69
	v_div_fmas_f32 v67, v67, v68, v70
	v_lshl_add_u64 v[68:69], s[4:5], 0, v[146:147]
	s_lshl_b32 s4, s29, 1
	s_add_u32 s4, s23, s4
	s_addc_u32 s5, s24, 0
	v_lshlrev_b64 v[68:69], 11, v[68:69]
	v_div_fixup_f32 v66, v67, v66, 1.0
	v_lshl_add_u64 v[68:69], s[4:5], 0, v[68:69]
	s_add_i32 s1, s1, s20
	s_add_i32 s27, s27, s28
	v_lshl_add_u64 v[68:69], v[68:69], 0, v[0:1]
	v_pk_mul_f32 v[62:63], v[66:67], v[62:63] op_sel_hi:[0,1]
	v_pk_mul_f32 v[58:59], v[66:67], v[58:59] op_sel_hi:[0,1]
	v_pk_mul_f32 v[54:55], v[66:67], v[54:55] op_sel_hi:[0,1]
	v_pk_mul_f32 v[50:51], v[66:67], v[50:51] op_sel_hi:[0,1]
	v_pk_mul_f32 v[46:47], v[66:67], v[46:47] op_sel_hi:[0,1]
	v_pk_mul_f32 v[42:43], v[66:67], v[42:43] op_sel_hi:[0,1]
	v_pk_mul_f32 v[38:39], v[66:67], v[38:39] op_sel_hi:[0,1]
	v_pk_mul_f32 v[34:35], v[66:67], v[34:35] op_sel_hi:[0,1]
	v_pk_mul_f32 v[30:31], v[66:67], v[30:31] op_sel_hi:[0,1]
	v_pk_mul_f32 v[26:27], v[66:67], v[26:27] op_sel_hi:[0,1]
	v_pk_mul_f32 v[22:23], v[66:67], v[22:23] op_sel_hi:[0,1]
	v_pk_mul_f32 v[18:19], v[66:67], v[18:19] op_sel_hi:[0,1]
	v_pk_mul_f32 v[14:15], v[66:67], v[14:15] op_sel_hi:[0,1]
	v_pk_mul_f32 v[10:11], v[66:67], v[10:11] op_sel_hi:[0,1]
	v_pk_mul_f32 v[6:7], v[66:67], v[6:7] op_sel_hi:[0,1]
	v_pk_mul_f32 v[2:3], v[66:67], v[2:3] op_sel_hi:[0,1]
	s_cmpk_gt_i32 s1, 0x7ff
	v_pk_mul_f32 v[64:65], v[66:67], v[64:65] op_sel_hi:[0,1]
	v_cvt_pk_bf16_f32 v62, v62, v63
	v_cvt_pk_bf16_f32 v63, v64, v65
	global_store_dwordx2 v[68:69], v[62:63], off
	v_pk_mul_f32 v[60:61], v[66:67], v[60:61] op_sel_hi:[0,1]
	v_cvt_pk_bf16_f32 v58, v58, v59
	v_cvt_pk_bf16_f32 v59, v60, v61
	global_store_dwordx2 v[68:69], v[58:59], off offset:32
	v_pk_mul_f32 v[56:57], v[66:67], v[56:57] op_sel_hi:[0,1]
	v_cvt_pk_bf16_f32 v54, v54, v55
	v_cvt_pk_bf16_f32 v55, v56, v57
	global_store_dwordx2 v[68:69], v[54:55], off offset:64
	v_pk_mul_f32 v[52:53], v[66:67], v[52:53] op_sel_hi:[0,1]
	v_cvt_pk_bf16_f32 v50, v50, v51
	v_cvt_pk_bf16_f32 v51, v52, v53
	global_store_dwordx2 v[68:69], v[50:51], off offset:96
	v_pk_mul_f32 v[48:49], v[66:67], v[48:49] op_sel_hi:[0,1]
	v_cvt_pk_bf16_f32 v46, v46, v47
	v_cvt_pk_bf16_f32 v47, v48, v49
	global_store_dwordx2 v[68:69], v[46:47], off offset:128
	v_pk_mul_f32 v[44:45], v[66:67], v[44:45] op_sel_hi:[0,1]
	v_cvt_pk_bf16_f32 v42, v42, v43
	v_cvt_pk_bf16_f32 v43, v44, v45
	global_store_dwordx2 v[68:69], v[42:43], off offset:160
	v_pk_mul_f32 v[40:41], v[66:67], v[40:41] op_sel_hi:[0,1]
	v_cvt_pk_bf16_f32 v38, v38, v39
	v_cvt_pk_bf16_f32 v39, v40, v41
	global_store_dwordx2 v[68:69], v[38:39], off offset:192
	v_pk_mul_f32 v[36:37], v[66:67], v[36:37] op_sel_hi:[0,1]
	v_cvt_pk_bf16_f32 v34, v34, v35
	v_cvt_pk_bf16_f32 v35, v36, v37
	global_store_dwordx2 v[68:69], v[34:35], off offset:224
	v_pk_mul_f32 v[32:33], v[66:67], v[32:33] op_sel_hi:[0,1]
	v_cvt_pk_bf16_f32 v30, v30, v31
	v_cvt_pk_bf16_f32 v31, v32, v33
	global_store_dwordx2 v[68:69], v[30:31], off offset:256
	v_pk_mul_f32 v[28:29], v[66:67], v[28:29] op_sel_hi:[0,1]
	v_cvt_pk_bf16_f32 v26, v26, v27
	v_cvt_pk_bf16_f32 v27, v28, v29
	global_store_dwordx2 v[68:69], v[26:27], off offset:288
	v_pk_mul_f32 v[24:25], v[66:67], v[24:25] op_sel_hi:[0,1]
	v_cvt_pk_bf16_f32 v22, v22, v23
	v_cvt_pk_bf16_f32 v23, v24, v25
	global_store_dwordx2 v[68:69], v[22:23], off offset:320
	v_pk_mul_f32 v[20:21], v[66:67], v[20:21] op_sel_hi:[0,1]
	v_cvt_pk_bf16_f32 v18, v18, v19
	v_cvt_pk_bf16_f32 v19, v20, v21
	global_store_dwordx2 v[68:69], v[18:19], off offset:352
	v_pk_mul_f32 v[16:17], v[66:67], v[16:17] op_sel_hi:[0,1]
	v_cvt_pk_bf16_f32 v14, v14, v15
	v_cvt_pk_bf16_f32 v15, v16, v17
	global_store_dwordx2 v[68:69], v[14:15], off offset:384
	v_pk_mul_f32 v[12:13], v[66:67], v[12:13] op_sel_hi:[0,1]
	v_cvt_pk_bf16_f32 v10, v10, v11
	v_cvt_pk_bf16_f32 v11, v12, v13
	global_store_dwordx2 v[68:69], v[10:11], off offset:416
	v_pk_mul_f32 v[8:9], v[66:67], v[8:9] op_sel_hi:[0,1]
	v_cvt_pk_bf16_f32 v6, v6, v7
	v_cvt_pk_bf16_f32 v7, v8, v9
	global_store_dwordx2 v[68:69], v[6:7], off offset:448
	v_pk_mul_f32 v[4:5], v[66:67], v[4:5] op_sel_hi:[0,1]
	v_cvt_pk_bf16_f32 v2, v2, v3
	v_cvt_pk_bf16_f32 v3, v4, v5
	global_store_dwordx2 v[68:69], v[2:3], off offset:480
	s_cbranch_scc1 .LBB0_608
; template <int D, int DV, int MODE, int NMAP, int KT> ...
;     ...
;     { const bf16_t* qr = Qp + (size_t)(w * 16 + r) * ldq + g4 * 8;
; #pragma unroll
;       for (int mp = 0; mp < NMAP; ++mp)
; #pragma unroll
;         for (int kk = 0; kk < D / 32; ++kk) qf[mp][kk] = *(const bf16x8*)(qr + mp * D + kk * 32); }
;     float m[NMAP];
; #pragma unroll
;     for (int mp = 0; mp < NMAP; ++mp) { m[mp] = -INFINITY; l[mp] = 0.f;
; #pragma unroll
;         for (int cb = 0; cb < DV / 16; ++cb) o[mp][cb] = (f32x4){0.f, 0.f, 0.f, 0.f}; }
;     const int rowmin = q0 + w * 16, myrow = rowmin + r;
;     float ck[NB][4];
;     if (MODE == 2) {
; #pragma unroll
;         for (int nb = 0; nb < NB; ++nb)
; #pragma unroll
;             for (int j = 0; j < 4; ++j) ck[nb][j] = __builtin_amdgcn_exp2f(-l2g * (float)(nb * 16 + g4 * 4 + j));
;     }
;     u32x4 kreg[KN], vreg[VN];
; __global__ void __launch_bounds__(512, 2) mega_fwd(Params P) {
;     ...
;                     for (int u = blk; u < 2048; u += G) {
;                         const int bh = u & 127, b = bh >> 2, h = bh & 3, qt = u >> 7, q0 = qt * 128;
;                         const size_t rb = (size_t)b * SEQ;
;                         f32x4 o[1][16]; float ll[1];
;                         attn_core3<256, 256, 0, 1, 64>(lds, BIG + (rb + q0) * 1024 + h * 256, 1024, KV + (size_t)b * 256 * 2048 + h * 256, 2048, KV + (size_t)b * 256 * 2048 + 1024 + h * 256, 2048, q0, 4, 0.0625f * LOG2E, 0.f, o, ll);
.LBB0_600:
	s_lshl_b32 s4, s27, 1
	s_and_b32 s94, s4, 0x600
	s_bfe_u32 s4, s1, 0x50002
	s_and_b32 s5, s1, 0xffffff80
	s_lshl_b32 s14, s4, 20
	s_lshl_b32 s4, s4, 11
	s_ashr_i32 s6, s5, 31
	s_add_u32 s4, s4, s5
	s_addc_u32 s5, 0, s6
	s_lshl_b64 s[6:7], s[4:5], 11
	s_add_u32 s6, s21, s6
	s_addc_u32 s7, s22, s7
	s_lshl_b32 s8, s1, 8
	s_and_b32 s29, s8, 0x300
	v_mov_b32_e32 v66, v211
	s_lshl_b32 s10, s29, 1
	s_add_u32 s8, s6, s10
	v_ashrrev_i32_e32 v2, 31, v66
	v_lshrrev_b32_e32 v2, 27, v2
	s_addc_u32 s9, s7, 0
	v_add_u32_e32 v2, v66, v2
	s_add_u32 s6, s25, s14
	v_ashrrev_i32_e32 v56, 5, v2
	v_and_b32_e32 v2, 0xffffffe0, v2
	s_addc_u32 s7, s26, 0
	v_sub_u32_e32 v98, v66, v2
	s_add_u32 s12, s6, s10
	v_ashrrev_i32_e32 v57, 31, v56
	v_lshlrev_b32_e32 v4, 3, v98
	s_addc_u32 s13, s7, 0
	v_lshlrev_b64 v[2:3], 12, v[56:57]
	v_ashrrev_i32_e32 v5, 31, v4
	v_lshl_add_u64 v[6:7], s[12:13], 0, v[2:3]
	v_lshlrev_b64 v[4:5], 1, v[4:5]
	v_lshl_add_u64 v[18:19], v[6:7], 0, v[4:5]
	v_add_u32_e32 v6, 0x200, v66
	v_ashrrev_i32_e32 v7, 31, v6
	v_lshrrev_b32_e32 v7, 27, v7
	v_add_u32_e32 v7, v6, v7
	v_ashrrev_i32_e32 v58, 5, v7
	v_and_b32_e32 v7, 0xffffffe0, v7
	v_sub_u32_e32 v57, v6, v7
	v_ashrrev_i32_e32 v59, 31, v58
	v_lshlrev_b32_e32 v8, 3, v57
	v_lshlrev_b64 v[6:7], 12, v[58:59]
	v_ashrrev_i32_e32 v9, 31, v8
	v_lshl_add_u64 v[10:11], s[12:13], 0, v[6:7]
	v_lshlrev_b64 v[8:9], 1, v[8:9]
	v_lshl_add_u64 v[20:21], v[10:11], 0, v[8:9]
	v_add_u32_e32 v10, 0x400, v66
	v_ashrrev_i32_e32 v11, 31, v10
	v_lshrrev_b32_e32 v11, 27, v11
	v_add_u32_e32 v11, v10, v11
	v_ashrrev_i32_e32 v60, 5, v11
	v_and_b32_e32 v11, 0xffffffe0, v11
	v_sub_u32_e32 v59, v10, v11
	v_ashrrev_i32_e32 v61, 31, v60
	v_lshlrev_b32_e32 v12, 3, v59
	v_lshlrev_b64 v[10:11], 12, v[60:61]
	v_ashrrev_i32_e32 v13, 31, v12
	v_lshl_add_u64 v[14:15], s[12:13], 0, v[10:11]
	v_lshlrev_b64 v[12:13], 1, v[12:13]
	v_readfirstlane_b32 s6, v66
	v_lshl_add_u64 v[62:63], v[14:15], 0, v[12:13]
	v_add_u32_e32 v14, 0x600, v66
	s_ashr_i32 s15, s6, 6
	v_ashrrev_i32_e32 v15, 31, v14
	v_lshrrev_b32_e32 v15, 27, v15
	s_ashr_i32 s6, s15, 31
	v_add_u32_e32 v15, v14, v15
	s_lshr_b32 s6, s6, 27
	s_add_i32 s10, s15, 8
	v_ashrrev_i32_e32 v64, 5, v15
	s_add_i32 s6, s15, s6
	s_ashr_i32 s11, s10, 31
	v_and_b32_e32 v160, 15, v66
	v_and_b32_e32 v15, 0xffffffe0, v15
	v_ashrrev_i32_e32 v65, 31, v64
	s_ashr_i32 s31, s6, 5
	s_andn2_b32 s6, s6, 31
	s_lshr_b32 s11, s11, 27
	s_add_i32 s16, s15, 16
	v_lshl_or_b32 v54, s15, 4, v160
	v_sub_u32_e32 v61, v14, v15
	v_lshlrev_b64 v[14:15], 12, v[64:65]
	v_and_b32_e32 v65, 63, v66
	s_sub_i32 s30, s15, s6
	s_lshl_b32 s45, s31, 6
	s_add_i32 s11, s10, s11
	s_ashr_i32 s17, s16, 31
	s_add_i32 s15, s15, 24
	v_lshlrev_b32_e32 v16, 3, v61
	v_or_b32_e32 v38, s45, v65
	s_ashr_i32 s34, s11, 5
	s_lshr_b32 s17, s17, 27
	s_ashr_i32 s18, s15, 31
	global_load_dwordx4 v[22:25], v[18:19], off
	global_load_dwordx4 v[26:29], v[20:21], off
	v_ashrrev_i32_e32 v17, 31, v16
	v_ashrrev_i32_e32 v39, 31, v38
	s_lshl_b32 s6, s30, 3
	s_andn2_b32 s11, s11, 31
	s_lshl_b32 s46, s34, 6
	s_add_i32 s17, s16, s17
	s_lshr_b32 s18, s18, 27
	v_lshl_add_u64 v[30:31], s[12:13], 0, v[14:15]
	v_lshlrev_b64 v[16:17], 1, v[16:17]
	v_lshlrev_b64 v[38:39], 12, v[38:39]
	s_ashr_i32 s7, s6, 31
	s_sub_i32 s33, s10, s11
	v_or_b32_e32 v40, s46, v65
	s_ashr_i32 s41, s17, 5
	s_add_i32 s18, s15, s18
	v_lshl_add_u64 v[106:107], v[30:31], 0, v[16:17]
	global_load_dwordx4 v[30:33], v[62:63], off
	global_load_dwordx4 v[34:37], v[106:107], off
	v_lshl_add_u64 v[38:39], s[12:13], 0, v[38:39]
	s_lshl_b64 s[6:7], s[6:7], 1
	v_ashrrev_i32_e32 v41, 31, v40
	s_lshl_b32 s10, s33, 3
	s_andn2_b32 s17, s17, 31
	s_lshl_b32 s47, s41, 6
	s_ashr_i32 s43, s18, 5
	v_lshl_add_u64 v[38:39], v[38:39], 0, s[6:7]
	v_lshlrev_b64 v[40:41], 12, v[40:41]
	s_ashr_i32 s11, s10, 31
	s_sub_i32 s40, s16, s17
	v_or_b32_e32 v46, s47, v65
	s_andn2_b32 s18, s18, 31
	s_lshl_b32 s48, s43, 6
	v_lshl_add_u64 v[42:43], s[12:13], 0, v[40:41]
	global_load_dwordx4 v[38:41], v[38:39], off offset:2048
	s_lshl_b64 s[10:11], s[10:11], 1
	v_ashrrev_i32_e32 v47, 31, v46
	s_lshl_b32 s16, s40, 3
	s_sub_i32 s42, s15, s18
	v_or_b32_e32 v50, s48, v65
	v_lshl_add_u64 v[42:43], v[42:43], 0, s[10:11]
	v_lshlrev_b64 v[46:47], 12, v[46:47]
	s_ashr_i32 s17, s16, 31
	v_ashrrev_i32_e32 v51, 31, v50
	s_lshl_b32 s18, s42, 3
	global_load_dwordx4 v[42:45], v[42:43], off offset:2048
	v_lshl_add_u64 v[46:47], s[12:13], 0, v[46:47]
	s_lshl_b64 s[16:17], s[16:17], 1
	v_lshlrev_b64 v[50:51], 12, v[50:51]
	s_ashr_i32 s19, s18, 31
	v_lshl_add_u64 v[46:47], v[46:47], 0, s[16:17]
	v_lshl_add_u64 v[50:51], s[12:13], 0, v[50:51]
	s_lshl_b64 s[18:19], s[18:19], 1
	global_load_dwordx4 v[46:49], v[46:47], off offset:2048
	v_lshl_add_u64 v[50:51], v[50:51], 0, s[18:19]
	global_load_dwordx4 v[50:53], v[50:51], off offset:2048
	v_ashrrev_i32_e32 v55, 31, v54
	v_lshrrev_b32_e32 v66, 1, v66
	v_lshlrev_b64 v[54:55], 11, v[54:55]
	v_and_b32_e32 v158, 24, v66
	v_lshl_add_u64 v[54:55], s[8:9], 0, v[54:55]
	v_lshlrev_b32_e32 v148, 1, v158
	v_mov_b32_e32 v149, v1
	v_lshl_add_u64 v[54:55], v[54:55], 0, v[148:149]
	v_mul_lo_u32 v161, v56, s66
	v_lshlrev_b32_e32 v162, 4, v98
	global_load_dwordx4 v[66:69], v[54:55], off
	global_load_dwordx4 v[70:73], v[54:55], off offset:64
	global_load_dwordx4 v[74:77], v[54:55], off offset:128
	global_load_dwordx4 v[78:81], v[54:55], off offset:192
	global_load_dwordx4 v[82:85], v[54:55], off offset:256
	global_load_dwordx4 v[86:89], v[54:55], off offset:320
	global_load_dwordx4 v[90:93], v[54:55], off offset:384
	global_load_dwordx4 v[94:97], v[54:55], off offset:448
	v_lshrrev_b32_e32 v169, 2, v56
	v_lshrrev_b32_e32 v163, 3, v56
	v_xor_b32_e32 v169, v169, v163
	v_and_b32_e32 v169, 1, v169
	v_lshlrev_b32_e32 v169, 4, v169
	v_xor_b32_e32 v162, v162, v169
	v_add3_u32 v54, 0, v161, v162
	v_mul_lo_u32 v163, v58, s66
	v_lshlrev_b32_e32 v164, 4, v57
	v_xor_b32_e32 v164, v164, v169
	s_waitcnt lgkmcnt(0)
	s_barrier
; template <int D, int DV, int MODE, int NMAP, int KT> ...
;     ...
;     for (int mp = 0; mp < NMAP; ++mp) { m[mp] = -INFINITY; l[mp] = 0.f;
; #pragma unroll
;         for (int cb = 0; cb < DV / 16; ++cb) o[mp][cb] = (f32x4){0.f, 0.f, 0.f, 0.f}; }
;     const int rowmin = q0 + w * 16, myrow = rowmin + r;
;     float ck[NB][4];
;     if (MODE == 2) {
; #pragma unroll
;         for (int nb = 0; nb < NB; ++nb)
; #pragma unroll
;             for (int j = 0; j < 4; ++j) ck[nb][j] = __builtin_amdgcn_exp2f(-l2g * (float)(nb * 16 + g4 * 4 + j));
;     }
;     u32x4 kreg[KN], vreg[VN];
;     ...
;     AT_LOAD(0);
;     __syncthreads();
;     AT_STORE(0);
;     if (nkt > 1) AT_LOAD(1);
	v_mul_lo_u32 v165, v60, s66
	v_lshlrev_b32_e32 v166, 4, v59
	v_xor_b32_e32 v166, v166, v169
	s_mulk_i32 s30, 0x480
	v_mul_lo_u32 v167, v64, s66
	v_lshlrev_b32_e32 v168, 4, v61
	v_xor_b32_e32 v168, v168, v169
	s_add_i32 s8, s30, 0
	s_lshl_b32 s31, s31, 7
	s_waitcnt vmcnt(0)
	ds_write_b128 v54, v[22:25]
	v_add3_u32 v22, 0, v163, v164
	ds_write_b128 v22, v[26:29]
	v_add3_u32 v22, 0, v165, v166
	s_add_i32 s8, s8, s31
	v_lshlrev_b32_e32 v169, 1, v65
	s_mulk_i32 s33, 0x480
	s_lshl_b32 s34, s34, 7
	s_mulk_i32 s40, 0x480
	s_lshl_b32 s41, s41, 7
	s_mulk_i32 s42, 0x480
	s_lshl_b32 s43, s43, 7
	v_add_co_u32_e32 v18, vcc, s35, v18
	s_mov_b32 s15, s95
	s_nop 0
	v_addc_co_u32_e32 v19, vcc, 0, v19, vcc
	ds_write_b128 v22, v[30:33]
	v_add3_u32 v22, 0, v167, v168
	ds_write_b128 v22, v[34:37]
	v_add_u32_e32 v22, s8, v169
	s_add_i32 s8, s33, 0
	s_add_i32 s8, s8, s34
	ds_write_b16 v22, v38 offset:33792
	ds_write_b16_d16_hi v22, v38 offset:33936
	ds_write_b16 v22, v39 offset:34080
	ds_write_b16_d16_hi v22, v39 offset:34224
	ds_write_b16 v22, v40 offset:34368
	ds_write_b16_d16_hi v22, v40 offset:34512
	ds_write_b16 v22, v41 offset:34656
	ds_write_b16_d16_hi v22, v41 offset:34800
	v_add_u32_e32 v22, s8, v169
	s_add_i32 s8, s40, 0
	s_add_i32 s8, s8, s41
	ds_write_b16 v22, v42 offset:33792
	ds_write_b16_d16_hi v22, v42 offset:33936
	ds_write_b16 v22, v43 offset:34080
	ds_write_b16_d16_hi v22, v43 offset:34224
	ds_write_b16 v22, v44 offset:34368
	ds_write_b16_d16_hi v22, v44 offset:34512
	ds_write_b16 v22, v45 offset:34656
	ds_write_b16_d16_hi v22, v45 offset:34800
	v_add_u32_e32 v22, s8, v169
	s_add_i32 s8, s42, 0
	s_add_i32 s8, s8, s43
	ds_write_b16 v22, v46 offset:33792
	ds_write_b16_d16_hi v22, v46 offset:33936
	ds_write_b16 v22, v47 offset:34080
	ds_write_b16_d16_hi v22, v47 offset:34224
	ds_write_b16 v22, v48 offset:34368
	ds_write_b16_d16_hi v22, v48 offset:34512
	ds_write_b16 v22, v49 offset:34656
	ds_write_b16_d16_hi v22, v49 offset:34800
	v_add_u32_e32 v22, s8, v169
	v_add_co_u32_e32 v20, vcc, s35, v20
	ds_write_b16 v22, v50 offset:33792
	ds_write_b16_d16_hi v22, v50 offset:33936
	ds_write_b16 v22, v51 offset:34080
	ds_write_b16_d16_hi v22, v51 offset:34224
	ds_write_b16 v22, v52 offset:34368
	ds_write_b16_d16_hi v22, v52 offset:34512
	ds_write_b16 v22, v53 offset:34656
	ds_write_b16_d16_hi v22, v53 offset:34800
	v_addc_co_u32_e32 v21, vcc, 0, v21, vcc
	global_load_dwordx4 v[98:101], v[18:19], off
	global_load_dwordx4 v[102:105], v[20:21], off
	v_add_co_u32_e32 v18, vcc, s35, v62
	v_or_b32_e32 v22, 64, v65
	s_nop 0
	v_addc_co_u32_e32 v19, vcc, 0, v63, vcc
	v_add_co_u32_e32 v20, vcc, s35, v106
	v_lshl_add_u64 v[14:15], s[14:15], 0, v[14:15]
	s_nop 0
	v_addc_co_u32_e32 v21, vcc, 0, v107, vcc
	global_load_dwordx4 v[106:109], v[18:19], off
	global_load_dwordx4 v[110:113], v[20:21], off
	v_add_u32_e32 v18, s45, v22
	v_ashrrev_i32_e32 v19, 31, v18
	v_add_u32_e32 v20, s46, v22
	v_lshlrev_b64 v[18:19], 12, v[18:19]
	v_ashrrev_i32_e32 v21, 31, v20
	v_lshl_add_u64 v[18:19], s[12:13], 0, v[18:19]
	v_lshlrev_b64 v[20:21], 12, v[20:21]
	v_lshl_add_u64 v[18:19], v[18:19], 0, s[6:7]
	v_lshl_add_u64 v[20:21], s[12:13], 0, v[20:21]
	v_lshl_add_u64 v[20:21], v[20:21], 0, s[10:11]
	global_load_dwordx4 v[114:117], v[18:19], off offset:2048
	global_load_dwordx4 v[118:121], v[20:21], off offset:2048
	v_add_u32_e32 v18, s47, v22
	v_ashrrev_i32_e32 v19, 31, v18
	v_add_u32_e32 v20, s48, v22
	v_lshlrev_b64 v[18:19], 12, v[18:19]
	v_ashrrev_i32_e32 v21, 31, v20
	v_lshl_add_u64 v[18:19], s[12:13], 0, v[18:19]
	v_lshlrev_b64 v[20:21], 12, v[20:21]
	v_lshl_add_u64 v[18:19], v[18:19], 0, s[16:17]
	v_lshl_add_u64 v[20:21], s[12:13], 0, v[20:21]
	v_lshl_add_u64 v[20:21], v[20:21], 0, s[18:19]
	global_load_dwordx4 v[122:125], v[18:19], off offset:2048
	global_load_dwordx4 v[126:129], v[20:21], off offset:2048
	s_add_u32 s6, s12, s6
	s_addc_u32 s7, s13, s7
	s_add_u32 s8, s12, s10
	s_addc_u32 s9, s13, s11
	s_add_u32 s10, s12, s16
	s_addc_u32 s11, s13, s17
	s_add_u32 s12, s12, s18
	v_lshl_add_u64 v[10:11], s[14:15], 0, v[10:11]
	v_lshl_add_u64 v[6:7], s[14:15], 0, v[6:7]
	v_lshl_add_u64 v[2:3], s[14:15], 0, v[2:3]
	s_addc_u32 s13, s13, s19
	s_addk_i32 s48, 0x80
	s_addk_i32 s47, 0x80
	s_addk_i32 s46, 0x80
	s_addk_i32 s45, 0x80
	v_lshl_add_u64 v[14:15], v[14:15], 0, v[16:17]
	v_lshl_add_u64 v[10:11], v[10:11], 0, v[12:13]
	v_lshl_add_u64 v[6:7], v[6:7], 0, v[8:9]
	v_lshl_add_u64 v[2:3], v[2:3], 0, v[4:5]
	v_mov_b32_e32 v4, v1
	v_mov_b32_e32 v5, v1
	v_or_b32_e32 v171, s48, v65
	v_or_b32_e32 v172, s47, v65
	v_or_b32_e32 v173, s46, v65
	v_or_b32_e32 v174, s45, v65
	v_lshl_add_u64 v[150:151], s[2:3], 0, v[14:15]
	v_lshl_add_u64 v[152:153], s[2:3], 0, v[10:11]
	v_lshl_add_u64 v[154:155], s[2:3], 0, v[6:7]
	v_lshl_add_u64 v[156:157], s[2:3], 0, v[2:3]
	v_mov_b32_e32 v2, v1
	v_mov_b32_e32 v3, v1
	v_mov_b64_e32 v[8:9], v[4:5]
	v_mov_b64_e32 v[12:13], v[4:5]
	v_mov_b64_e32 v[16:17], v[4:5]
	v_mov_b64_e32 v[20:21], v[4:5]
	v_mov_b64_e32 v[24:25], v[4:5]
	v_mov_b64_e32 v[28:29], v[4:5]
	v_mov_b64_e32 v[32:33], v[4:5]
	v_mov_b64_e32 v[36:37], v[4:5]
	v_mov_b64_e32 v[40:41], v[4:5]
	v_mov_b64_e32 v[44:45], v[4:5]
	v_mov_b64_e32 v[48:49], v[4:5]
	v_mov_b64_e32 v[52:53], v[4:5]
	v_mov_b64_e32 v[56:57], v[4:5]
	v_mov_b64_e32 v[60:61], v[4:5]
	v_mov_b64_e32 v[64:65], v[4:5]
	s_mov_b32 s44, 0
	v_mul_u32_u24_e32 v170, 0x210, v160
	v_lshrrev_b32_e32 v149, 2, v160
	v_lshrrev_b32_e32 v175, 3, v160
	v_xor_b32_e32 v149, v149, v175
	v_and_b32_e32 v149, 1, v149
	v_lshlrev_b32_e32 v149, 3, v149
	v_xor_b32_e32 v175, v149, v158
	v_sub_u32_e32 v175, v175, v158
	v_lshlrev_b32_e32 v175, 1, v175
	v_add_u32_e32 v170, v170, v175
	v_mul_u32_u24_e32 v149, 0x90, v160
	v_readlane_b32 s46, v254, 1
	v_mov_b32_e32 v175, 0xff800000
	v_mov_b32_e32 v159, 0
	v_mov_b64_e32 v[6:7], v[2:3]
	v_mov_b64_e32 v[10:11], v[2:3]
	v_mov_b64_e32 v[14:15], v[2:3]
	v_mov_b64_e32 v[18:19], v[2:3]
	v_mov_b64_e32 v[22:23], v[2:3]
	v_mov_b64_e32 v[26:27], v[2:3]
	v_mov_b64_e32 v[30:31], v[2:3]
	v_mov_b64_e32 v[34:35], v[2:3]
	v_mov_b64_e32 v[38:39], v[2:3]
	v_mov_b64_e32 v[42:43], v[2:3]
	v_mov_b64_e32 v[46:47], v[2:3]
	v_mov_b64_e32 v[50:51], v[2:3]
	v_mov_b64_e32 v[54:55], v[2:3]
	v_mov_b64_e32 v[58:59], v[2:3]
	v_mov_b64_e32 v[62:63], v[2:3]
	s_mov_b32 s15, 0
	v_readlane_b32 s47, v254, 2

; __device__ __forceinline__ unsigned cvt_pk_bf16(float lo, float hi) { unsigned r; asm volatile("v_cvt_pk_bf16_f32 %0, %1, %2" : "=v"(r) : "v"(lo), "v"(hi)); return r; }
; template <int D, int DV, int MODE, int NMAP, int KT> ...
;     ...
;                     const float nm = -m[mp]; float ps = 0.f;
; #pragma unroll
;                     for (int nb = 0; nb < NB; ++nb)
; #pragma unroll
;                         for (int j = 0; j < 4; ++j) { const float p = __builtin_amdgcn_exp2f(fmaf(s[nb][j], sc, nm)); ps += p; s[nb][j] = p; }
;                     l[mp] += ps;
;                 } else {
;                     const float rowf = __builtin_amdgcn_exp2f(l2g * (float)(myrow - kt * KT));
; #pragma unroll
;                     for (int nb = 0; nb < NB; ++nb)
; #pragma unroll
;                         for (int j = 0; j < 4; ++j) { float p = s[nb][j] * (rowf * ck[nb][j]); if (diag && (kt * KT + nb * 16 + g4 * 4 + j > myrow)) p = 0.f; s[nb][j] = p; }
;                 }
; #pragma unroll
;                 for (int kk = 0; kk < KK2; ++kk) { u32x4 wv; wv.x = cvt_pk_bf16(s[2 * kk][0], s[2 * kk][1]); wv.y = cvt_pk_bf16(s[2 * kk][2], s[2 * kk][3]);
;                     wv.z = cvt_pk_bf16(s[2 * kk + 1][0], s[2 * kk + 1][1]); wv.w = cvt_pk_bf16(s[2 * kk + 1][2], s[2 * kk + 1][3]); pb[mp][kk] = __builtin_bit_cast(bf16x8, wv); }
;             }
;             {
;                 constexpr int CBB = 4, NCB = (DV / 16) / CBB, NVB = KK2 * NCB;
;                 bf16x8 vfr[2][CBB];
;     ...
;                 AT_VLOAD(0, 0);
; #pragma unroll
;                 for (int b_ = 0; b_ < NVB; ++b_) {
;                     if (b_ + 1 < NVB) AT_VLOAD(b_ + 1, (b_ + 1) & 1);
;                     __builtin_amdgcn_sched_barrier(0);
;                     const int kk_ = b_ / NCB, c0_ = (b_ % NCB) * CBB;
;                     __builtin_amdgcn_s_setprio(1);
; #pragma unroll
;                     for (int x_ = 0; x_ < CBB; ++x_)
; #pragma unroll
;                         for (int mp = 0; mp < NMAP; ++mp) o[mp][c0_ + x_] = __builtin_amdgcn_mfma_f32_16x16x32_bf16(vfr[b_ & 1][x_], pb[mp][kk_], o[mp][c0_ + x_], 0, 0, 0);
;                     __builtin_amdgcn_s_setprio(0);
;                     __builtin_amdgcn_sched_barrier(0);
;                 }
.LBB0_605:
	v_fma_f32 v142, v142, s0, -v175
	v_exp_f32_e32 v142, v142
	v_fma_f32 v143, v143, s0, -v175
	v_exp_f32_e32 v143, v143
	v_fma_f32 v144, v144, s0, -v175
	v_exp_f32_e32 v144, v144
	v_fma_f32 v145, v145, s0, -v175
	v_exp_f32_e32 v145, v145
	v_fma_f32 v138, v138, s0, -v175
	v_add_f32_e32 v176, 0, v142
	v_exp_f32_e32 v138, v138
	v_fma_f32 v139, v139, s0, -v175
	v_add_f32_e32 v176, v143, v176
	v_exp_f32_e32 v139, v139
	v_fma_f32 v140, v140, s0, -v175
	v_add_f32_e32 v176, v144, v176
	v_exp_f32_e32 v140, v140
	v_fma_f32 v141, v141, s0, -v175
	v_add_f32_e32 v176, v145, v176
	v_exp_f32_e32 v141, v141
	v_fma_f32 v134, v134, s0, -v175
	v_add_f32_e32 v176, v138, v176
	v_exp_f32_e32 v177, v134
	v_add_f32_e32 v176, v139, v176
	v_add_f32_e32 v176, v140, v176
	v_add_f32_e32 v176, v141, v176
	v_fma_f32 v135, v135, s0, -v175
	v_add_f32_e32 v134, v177, v176
	v_exp_f32_e32 v176, v135
	v_fma_f32 v135, v136, s0, -v175
	v_exp_f32_e32 v178, v135
	v_fma_f32 v135, v137, s0, -v175
	v_exp_f32_e32 v179, v135
	v_fma_f32 v130, v130, s0, -v175
	v_exp_f32_e32 v180, v130
	v_fma_f32 v131, v131, s0, -v175
	v_add_f32_e32 v134, v176, v134
	v_exp_f32_e32 v181, v131
	v_fma_f32 v131, v132, s0, -v175
	v_add_f32_e32 v134, v178, v134
	v_exp_f32_e32 v182, v131
	v_fma_f32 v131, v133, s0, -v175
	v_add_f32_e32 v134, v179, v134
	v_exp_f32_e32 v133, v131
	v_add_f32_e32 v130, v180, v134
	v_add_f32_e32 v130, v181, v130
	v_add_f32_e32 v130, v182, v130
	v_add3_u32 v184, s15, v158, v149
	v_add_f32_e32 v130, v133, v130
	v_add_u32_e32 v210, 0x8000, v184
	v_add_u32_e32 v212, 0x8800, v184
	v_add_u32_e32 v213, 0x9000, v184
	v_add_u32_e32 v214, 0x9800, v184
	v_add_u32_e32 v215, 0xa800, v184
	v_add_u32_e32 v216, 0xb000, v184
	v_add_u32_e32 v217, 0xb800, v184
	v_add_u32_e32 v226, 0xc000, v184
	v_add_f32_e32 v159, v159, v130
	v_cvt_pk_bf16_f32 v134, v142, v143
	v_cvt_pk_bf16_f32 v135, v144, v145
	v_cvt_pk_bf16_f32 v136, v138, v139
	v_cvt_pk_bf16_f32 v137, v140, v141
	v_cvt_pk_bf16_f32 v130, v177, v176
	v_cvt_pk_bf16_f32 v131, v178, v179
	v_cvt_pk_bf16_f32 v132, v180, v181
	v_cvt_pk_bf16_f32 v133, v182, v133
	ds_read_b64 v[138:139], v210 offset:1024
	ds_read_b64 v[140:141], v210 offset:1056
	ds_read_b64 v[142:143], v212 offset:1280
	ds_read_b64 v[144:145], v212 offset:1312
	ds_read_b64 v[176:177], v213 offset:1536
	ds_read_b64 v[178:179], v213 offset:1568
	ds_read_b64 v[180:181], v214 offset:1792
	ds_read_b64 v[182:183], v214 offset:1824
	ds_read_b64 v[194:195], v215
	ds_read_b64 v[196:197], v215 offset:32
	ds_read_b64 v[198:199], v216 offset:256
	ds_read_b64 v[200:201], v216 offset:288
	ds_read_b64 v[202:203], v217 offset:512
	ds_read_b64 v[204:205], v217 offset:544
	ds_read_b64 v[206:207], v226 offset:768
	ds_read_b64 v[208:209], v226 offset:800
	v_add_u32_e32 v185, 0x8400, v184
	s_setprio 1
	s_waitcnt lgkmcnt(0)
	v_mfma_f32_16x16x32_bf16 v[62:65], v[138:141], v[134:137], v[62:65]
	v_mfma_f32_16x16x32_bf16 v[58:61], v[142:145], v[134:137], v[58:61]
	v_mfma_f32_16x16x32_bf16 v[54:57], v[176:179], v[134:137], v[54:57]
	v_mfma_f32_16x16x32_bf16 v[50:53], v[180:183], v[134:137], v[50:53]
	s_setprio 0
	v_add_u32_e32 v227, 0xc800, v184
	v_add_u32_e32 v228, 0xd000, v184
	v_add_u32_e32 v229, 0xd800, v184
	v_add_u32_e32 v230, 0xe000, v184
	ds_read_b64 v[138:139], v227 offset:1024
	ds_read_b64 v[140:141], v227 offset:1056
	ds_read_b64 v[142:143], v228 offset:1280
	ds_read_b64 v[144:145], v228 offset:1312
	ds_read_b64 v[176:177], v229 offset:1536
	ds_read_b64 v[178:179], v229 offset:1568
	ds_read_b64 v[180:181], v230 offset:1792
	ds_read_b64 v[182:183], v230 offset:1824
	s_setprio 1
	v_mfma_f32_16x16x32_bf16 v[46:49], v[194:197], v[134:137], v[46:49]
	v_mfma_f32_16x16x32_bf16 v[42:45], v[198:201], v[134:137], v[42:45]
	v_mfma_f32_16x16x32_bf16 v[38:41], v[202:205], v[134:137], v[38:41]
	v_mfma_f32_16x16x32_bf16 v[34:37], v[206:209], v[134:137], v[34:37]
	s_setprio 0
	v_add_u32_e32 v231, 0xf000, v184
	v_add_u32_e32 v232, 0xf800, v184
	v_add_u32_e32 v202, 0x7800, v185
	v_add_u32_e32 v185, 0x8000, v185
	ds_read_b64 v[194:195], v231
	ds_read_b64 v[196:197], v231 offset:32
	ds_read_b64 v[198:199], v232 offset:256
	ds_read_b64 v[200:201], v232 offset:288
	ds_read_b64 v[204:205], v202 offset:1568
	ds_read_b64 v[202:203], v202 offset:1536
	ds_read_b64 v[206:207], v185 offset:1792
	ds_read_b64 v[208:209], v185 offset:1824
	s_setprio 1
	s_waitcnt lgkmcnt(0)
; template <int D, int DV, int MODE, int NMAP, int KT> ...
;     ...
;                 constexpr int CBB = 4, NCB = (DV / 16) / CBB, NVB = KK2 * NCB;
;                 bf16x8 vfr[2][CBB];
;     ...
;                 AT_VLOAD(0, 0);
; #pragma unroll
;                 for (int b_ = 0; b_ < NVB; ++b_) {
;                     if (b_ + 1 < NVB) AT_VLOAD(b_ + 1, (b_ + 1) & 1);
;                     __builtin_amdgcn_sched_barrier(0);
;                     const int kk_ = b_ / NCB, c0_ = (b_ % NCB) * CBB;
;                     __builtin_amdgcn_s_setprio(1);
; #pragma unroll
;                     for (int x_ = 0; x_ < CBB; ++x_)
; #pragma unroll
;                         for (int mp = 0; mp < NMAP; ++mp) o[mp][c0_ + x_] = __builtin_amdgcn_mfma_f32_16x16x32_bf16(vfr[b_ & 1][x_], pb[mp][kk_], o[mp][c0_ + x_], 0, 0, 0);
;                     __builtin_amdgcn_s_setprio(0);
;                     __builtin_amdgcn_sched_barrier(0);
;                 }
	v_mfma_f32_16x16x32_bf16 v[30:33], v[138:141], v[134:137], v[30:33]
	v_mfma_f32_16x16x32_bf16 v[26:29], v[142:145], v[134:137], v[26:29]
	v_mfma_f32_16x16x32_bf16 v[22:25], v[176:179], v[134:137], v[22:25]
	v_mfma_f32_16x16x32_bf16 v[18:21], v[180:183], v[134:137], v[18:21]
	s_setprio 0
	ds_read_b64 v[138:139], v210 offset:1088
	ds_read_b64 v[140:141], v210 offset:1120
	ds_read_b64 v[142:143], v212 offset:1344
	ds_read_b64 v[144:145], v212 offset:1376
	ds_read_b64 v[176:177], v213 offset:1600
	ds_read_b64 v[178:179], v213 offset:1632
	ds_read_b64 v[180:181], v214 offset:1856
	ds_read_b64 v[182:183], v214 offset:1888
	v_add_u32_e32 v184, 0x8440, v184
	s_setprio 1
	v_mfma_f32_16x16x32_bf16 v[14:17], v[194:197], v[134:137], v[14:17]
	v_mfma_f32_16x16x32_bf16 v[10:13], v[198:201], v[134:137], v[10:13]
	v_mfma_f32_16x16x32_bf16 v[6:9], v[202:205], v[134:137], v[6:9]
	v_mfma_f32_16x16x32_bf16 v[2:5], v[206:209], v[134:137], v[2:5]
	s_setprio 0
	ds_read_b64 v[134:135], v215 offset:64
	ds_read_b64 v[136:137], v215 offset:96
	ds_read_b64 v[194:195], v216 offset:320
	ds_read_b64 v[196:197], v216 offset:352
	ds_read_b64 v[198:199], v217 offset:576
	ds_read_b64 v[200:201], v217 offset:608
	ds_read_b64 v[202:203], v226 offset:832
	ds_read_b64 v[204:205], v226 offset:864
	s_setprio 1
	s_waitcnt lgkmcnt(0)
	v_mfma_f32_16x16x32_bf16 v[62:65], v[138:141], v[130:133], v[62:65]
	v_mfma_f32_16x16x32_bf16 v[58:61], v[142:145], v[130:133], v[58:61]
	v_mfma_f32_16x16x32_bf16 v[54:57], v[176:179], v[130:133], v[54:57]
	v_mfma_f32_16x16x32_bf16 v[50:53], v[180:183], v[130:133], v[50:53]
	s_setprio 0
	ds_read_b64 v[138:139], v227 offset:1088
	ds_read_b64 v[140:141], v227 offset:1120
	ds_read_b64 v[142:143], v228 offset:1344
	ds_read_b64 v[144:145], v228 offset:1376
	ds_read_b64 v[176:177], v229 offset:1600
	ds_read_b64 v[178:179], v229 offset:1632
	ds_read_b64 v[180:181], v230 offset:1856
	ds_read_b64 v[182:183], v230 offset:1888
	s_setprio 1
	v_mfma_f32_16x16x32_bf16 v[46:49], v[134:137], v[130:133], v[46:49]
	v_mfma_f32_16x16x32_bf16 v[42:45], v[194:197], v[130:133], v[42:45]
	v_mfma_f32_16x16x32_bf16 v[38:41], v[198:201], v[130:133], v[38:41]
	v_mfma_f32_16x16x32_bf16 v[34:37], v[202:205], v[130:133], v[34:37]
	s_setprio 0
	ds_read_b64 v[134:135], v231 offset:64
	ds_read_b64 v[136:137], v231 offset:96
	ds_read_b64 v[194:195], v232 offset:320
	ds_read_b64 v[196:197], v232 offset:352
	v_add_u32_e32 v185, 0x7800, v184
	v_add_u32_e32 v184, 0x8000, v184
	ds_read_b64 v[198:199], v185 offset:1536
	ds_read_b64 v[200:201], v185 offset:1568
	ds_read_b64 v[202:203], v184 offset:1792
	ds_read_b64 v[204:205], v184 offset:1824
	s_setprio 1
	s_waitcnt lgkmcnt(0)
	v_mfma_f32_16x16x32_bf16 v[30:33], v[138:141], v[130:133], v[30:33]
	v_mfma_f32_16x16x32_bf16 v[26:29], v[142:145], v[130:133], v[26:29]
	v_mfma_f32_16x16x32_bf16 v[22:25], v[176:179], v[130:133], v[22:25]
	v_mfma_f32_16x16x32_bf16 v[18:21], v[180:183], v[130:133], v[18:21]
	s_setprio 0
	s_setprio 1
	v_mfma_f32_16x16x32_bf16 v[14:17], v[134:137], v[130:133], v[14:17]
	v_mfma_f32_16x16x32_bf16 v[10:13], v[194:197], v[130:133], v[10:13]
	v_mfma_f32_16x16x32_bf16 v[6:9], v[198:201], v[130:133], v[6:9]
	v_mfma_f32_16x16x32_bf16 v[2:5], v[202:205], v[130:133], v[2:5]
	s_setprio 0
	s_add_i32 s44, s44, 64
	v_lshl_add_u64 v[150:151], v[150:151], 0, s[72:73]
	v_lshl_add_u64 v[152:153], v[152:153], 0, s[72:73]
	v_lshl_add_u64 v[154:155], v[154:155], 0, s[72:73]
	s_cmpk_lg_i32 s44, 0xc0
	v_lshl_add_u64 v[156:157], v[156:157], 0, s[72:73]
	s_cbranch_scc0 .LBB0_597
	s_mov_b32 s15, s14
	s_branch .LBB0_601
